# MF workspace stored fragment-major so S5 Toeplitz/carry A-fragment loads read whole cache lines (on top of LDS-staged E@U)
# speedup vs baseline: 1.0081x; 1.0013x over previous
.LBB0_49:
	s_or_b64 exec, exec, s[54:55]
	v_cvt_pk_bf16_f32 v12, v3, v9
	v_lshrrev_b32_e32 v3, 5, v2
	v_lshlrev_b32_e32 v3, 15, v3
	v_and_b32_e32 v2, 31, v2
	v_lshl_add_u32 v3, v2, 5, v3
	v_lshrrev_b32_e32 v2, 4, v8
	v_lshl_add_u32 v3, v2, 10, v3
	v_and_b32_e32 v2, 8, v8
	v_lshl_add_u32 v66, v2, 1, v3
	v_lshl_add_u64 v[2:3], s[30:31], 0, v[66:67]
	s_movk_i32 s0, 0x3dff
	v_cvt_pk_bf16_f32 v13, v10, v11
	v_cvt_pk_bf16_f32 v14, v16, v17
	v_cvt_pk_bf16_f32 v15, v18, v19
	global_store_dwordx4 v[2:3], v[12:15], off
	v_add_u32_e32 v2, 0x200, v7
	v_cmp_lt_i32_e32 vcc, s0, v7
	v_add_u32_e32 v6, 0x1000, v6
	s_or_b64 s[52:53], vcc, s[52:53]
	v_mov_b32_e32 v7, v2
	s_andn2_b64 exec, exec, s[52:53]
	s_cbranch_execz .LBB0_101

.LBB0_716:
	s_mov_b64 s[6:7], s[50:51]
	s_nop 4
	v_mov_b32_e32 v0, v210
	s_and_b64 vcc, exec, s[2:3]
	s_cbranch_vccnz .LBB0_728
	v_and_b32_e32 v21, 31, v0
	v_ashrrev_i32_e32 v6, 6, v0
	v_lshlrev_b32_e32 v2, 4, v21
	v_lshl_or_b32 v2, v6, 14, v2
	v_ashrrev_i32_e32 v3, 31, v2
	v_bfe_u32 v1, v0, 5, 1
	v_lshlrev_b64 v[2:3], 1, v[2:3]
	s_waitcnt lgkmcnt(0)
	v_lshl_add_u64 v[4:5], s[6:7], 0, v[2:3]
	v_lshlrev_b32_e32 v32, 4, v1
	v_lshl_add_u64 v[4:5], v[4:5], 0, v[32:33]
	s_mov_b64 s[0:1], 0x45c1000
	v_lshl_add_u64 v[112:113], v[4:5], 0, s[0:1]
	v_lshlrev_b32_e32 v4, 4, v0
	v_and_b32_e32 v5, 0x1e0, v4
	v_and_b32_e32 v4, 16, v4
	v_add3_u32 v22, 0, v5, v4
	v_ashrrev_i32_e32 v4, 2, v0
	s_movk_i32 s0, 0xffe0
	v_lshlrev_b32_e32 v114, 1, v6
	v_and_b32_e32 v6, 0xffffffe0, v4
	v_bfi_b32 v119, s0, v4, v0
	v_lshl_add_u64 v[4:5], s[6:7], 0, v[32:33]
	s_mov_b64 s[0:1], 0x3dc0000
	v_lshl_add_u64 v[116:117], v[4:5], 0, s[0:1]
	v_lshlrev_b32_e32 v4, 2, v6
	v_readlane_b32 s8, v255, 29
	v_add_u32_e32 v6, 0x200, v0
	v_ashrrev_i32_e32 v7, 31, v6
	v_add3_u32 v5, s8, v4, v32
	v_lshlrev_b32_e32 v4, 2, v1
	v_ashrrev_i32_e32 v1, 31, v0
	v_lshlrev_b64 v[120:121], 4, v[0:1]
	v_ashrrev_i32_e32 v1, 5, v0
	s_movk_i32 s9, 0x210
	v_lshlrev_b64 v[122:123], 4, v[6:7]
	v_add_u32_e32 v8, 0x400, v0
	v_mul_lo_u32 v7, v1, s9
	v_ashrrev_i32_e32 v1, 5, v6
	v_ashrrev_i32_e32 v9, 31, v8
	v_add_u32_e32 v10, 0x600, v0
	v_mul_lo_u32 v6, v1, s9
	v_ashrrev_i32_e32 v1, 5, v8
	v_lshlrev_b64 v[124:125], 4, v[8:9]
	v_add_u32_e32 v12, 0x800, v0
	v_mul_lo_u32 v8, v1, s9
	v_ashrrev_i32_e32 v1, 5, v10
	v_ashrrev_i32_e32 v11, 31, v10
	v_add_u32_e32 v14, 0xa00, v0
	v_mul_lo_u32 v9, v1, s9
	v_ashrrev_i32_e32 v1, 5, v12
	s_add_u32 s12, s6, 0x2a5d0000
	v_lshlrev_b64 v[126:127], 4, v[10:11]
	v_add_u32_e32 v16, 0xc00, v0
	v_mul_lo_u32 v10, v1, s9
	v_ashrrev_i32_e32 v1, 5, v14
	s_addc_u32 s13, s7, 0
	v_ashrrev_i32_e32 v13, 31, v12
	v_add_u32_e32 v18, 0xe00, v0
	v_mul_lo_u32 v11, v1, s9
	v_ashrrev_i32_e32 v1, 5, v16
	s_add_u32 s14, s6, 0x2c5d0000
	v_lshlrev_b64 v[128:129], 4, v[12:13]
	v_mul_lo_u32 v12, v1, s9
	v_ashrrev_i32_e32 v1, 5, v18
	s_addc_u32 s15, s7, 0
	s_lshl_b32 s16, s90, 5
	v_mul_lo_u32 v13, v1, s9
	v_and_b32_e32 v1, 0x5f, v0
	v_and_b32_e32 v20, 63, v0
	v_cmp_gt_u32_e64 s[2:3], 64, v0
	s_add_u32 s0, s6, 0x55c0000
	v_mul_u32_u24_e32 v141, 0x210, v1
	v_lshlrev_b32_e32 v143, 1, v0
	v_mul_u32_u24_e32 v1, 0x210, v21
	v_and_b32_e32 v0, 32, v0
	v_or_b32_e32 v2, v2, v32
	v_add_u32_e32 v139, 0, v32
	s_addc_u32 s1, s7, 0
	v_lshlrev_b32_e32 v118, 4, v21
	v_ashrrev_i32_e32 v15, 31, v14
	v_ashrrev_i32_e32 v17, 31, v16
	v_ashrrev_i32_e32 v19, 31, v18
	v_or_b32_e32 v136, 1, v114
	v_add3_u32 v156, v1, v0, 0
	v_lshl_add_u64 v[0:1], s[6:7], 0, v[2:3]
	s_mov_b64 s[6:7], 0x45c5000
	v_lshlrev_b64 v[130:131], 4, v[14:15]
	v_lshlrev_b64 v[132:133], 4, v[16:17]
	v_lshlrev_b64 v[134:135], 4, v[18:19]
	v_mad_u32_u24 v154, v21, s9, v139
	v_ashrrev_i32_e32 v115, 31, v114
	v_ashrrev_i32_e32 v137, 31, v136
	v_or_b32_e32 v138, 0x200, v118
	v_or_b32_e32 v140, 0x400, v118
	v_or_b32_e32 v142, 0x600, v118
	v_lshl_add_u32 v155, v20, 2, s8
	v_lshl_add_u64 v[144:145], v[0:1], 0, s[6:7]
	v_add_u32_e32 v157, v22, v7
	v_add_u32_e32 v158, v22, v6
	v_add_u32_e32 v159, v22, v8
	v_add_u32_e32 v160, v22, v9
	v_add_u32_e32 v161, v22, v10
	v_add_u32_e32 v162, v22, v11
	v_add_u32_e32 v163, v22, v12
	v_add_u32_e32 v164, v22, v13
	v_add_u32_e32 v165, v5, v141
	v_lshlrev_b32_e32 v146, 1, v4
	s_mov_b32 s17, s26
	s_mov_b32 s6, s26

.LBB0_719:
	v_lshrrev_b32_e32 v44, 6, v210
	v_bfe_u32 v45, v210, 5, 1
	v_and_b32_e32 v46, 31, v210
	v_lshlrev_b32_e32 v34, 13, v44
	v_lshl_add_u32 v34, v45, 9, v34
	v_sub_u32_e32 v47, v46, v45
	v_lshl_add_u32 v34, v47, 4, v34
	s_lshl_b32 s24, s88, 9
	v_add_u32_e32 v34, s24, v34
	v_add_u32_e32 v34, 0x1000, v34
	v_mov_b32_e32 v35, v33
	v_lshl_add_u64 v[34:35], v[150:151], 0, v[34:35]
	global_load_dwordx4 v[166:169], v[34:35], off offset:-4096
	global_load_dwordx4 v[170:173], v[34:35], off offset:-3072
	global_load_dwordx4 v[174:177], v[34:35], off offset:-2048
	global_load_dwordx4 v[190:193], v[34:35], off offset:-1024
	global_load_dwordx4 v[194:197], v[34:35], off offset:0
	global_load_dwordx4 v[198:201], v[34:35], off offset:1024
	global_load_dwordx4 v[202:205], v[34:35], off offset:2048
	global_load_dwordx4 v[206:209], v[34:35], off offset:3072
	v_lshl_add_u32 v44, v44, 4, v45
	v_mul_u32_u24_e32 v44, 0x210, v44
	v_lshl_add_u32 v44, v46, 4, v44
	v_add_u32_e32 v44, 0x10800, v44
	v_mul_u32_u24_e32 v47, 0x210, v119
	v_lshl_add_u32 v45, v45, 4, v47
	v_add_u32_e32 v45, 0x10800, v45
	v_add_u32_e32 v32, v139, v141
	ds_read_b128 v[246:249], v32
	ds_read_b128 v[250:253], v32 offset:16896
	ds_read_b128 v[36:39], v32 offset:32
	ds_read_b128 v[40:43], v32 offset:16928
	s_waitcnt vmcnt(7)
	ds_write_b128 v44, v[166:169]
	s_waitcnt vmcnt(6)
	ds_write_b128 v44, v[170:173] offset:1056
	s_waitcnt vmcnt(5)
	ds_write_b128 v44, v[174:177] offset:2112
	s_waitcnt vmcnt(4)
	ds_write_b128 v44, v[190:193] offset:3168
	s_waitcnt vmcnt(3)
	ds_write_b128 v44, v[194:197] offset:4224
	s_waitcnt vmcnt(2)
	ds_write_b128 v44, v[198:201] offset:5280
	s_waitcnt vmcnt(1)
	ds_write_b128 v44, v[202:205] offset:6336
	s_waitcnt vmcnt(0)
	ds_write_b128 v44, v[206:209] offset:7392
	s_waitcnt lgkmcnt(0)
	s_barrier
	ds_read_b128 v[234:237], v45
	ds_read_b128 v[238:241], v45 offset:32
	ds_read_b128 v[242:245], v45 offset:64
	s_waitcnt lgkmcnt(2)
	v_mfma_f32_32x32x16_bf16 v[96:111], v[234:237], v[246:249], 0
	ds_read_b128 v[246:249], v32 offset:64
	s_waitcnt lgkmcnt(3)
	v_mfma_f32_32x32x16_bf16 v[80:95], v[234:237], v[250:253], 0
	ds_read_b128 v[250:253], v32 offset:16960
	ds_read_b128 v[234:237], v45 offset:96
	s_waitcnt lgkmcnt(4)
	v_mfma_f32_32x32x16_bf16 v[96:111], v[238:241], v[36:39], v[96:111]
	ds_read_b128 v[36:39], v32 offset:96
	s_waitcnt lgkmcnt(5)
	v_mfma_f32_32x32x16_bf16 v[80:95], v[238:241], v[40:43], v[80:95]
	ds_read_b128 v[40:43], v32 offset:16992
	ds_read_b128 v[238:241], v45 offset:128
	s_waitcnt lgkmcnt(5)
	v_mfma_f32_32x32x16_bf16 v[96:111], v[242:245], v[246:249], v[96:111]
	ds_read_b128 v[246:249], v32 offset:128
	s_waitcnt lgkmcnt(5)
	v_mfma_f32_32x32x16_bf16 v[80:95], v[242:245], v[250:253], v[80:95]
	ds_read_b128 v[250:253], v32 offset:17024
	ds_read_b128 v[242:245], v45 offset:160
	s_waitcnt lgkmcnt(5)
	v_mfma_f32_32x32x16_bf16 v[96:111], v[234:237], v[36:39], v[96:111]
	ds_read_b128 v[36:39], v32 offset:160
	s_waitcnt lgkmcnt(5)
	v_mfma_f32_32x32x16_bf16 v[80:95], v[234:237], v[40:43], v[80:95]
	ds_read_b128 v[40:43], v32 offset:17056
	ds_read_b128 v[234:237], v45 offset:192
	s_waitcnt lgkmcnt(5)
	v_mfma_f32_32x32x16_bf16 v[96:111], v[238:241], v[246:249], v[96:111]
	ds_read_b128 v[246:249], v32 offset:192
	s_waitcnt lgkmcnt(5)
	v_mfma_f32_32x32x16_bf16 v[80:95], v[238:241], v[250:253], v[80:95]
	ds_read_b128 v[250:253], v32 offset:17088
	ds_read_b128 v[238:241], v45 offset:224
	s_waitcnt lgkmcnt(5)
	v_mfma_f32_32x32x16_bf16 v[96:111], v[242:245], v[36:39], v[96:111]
	ds_read_b128 v[36:39], v32 offset:224
	s_waitcnt lgkmcnt(5)
	v_mfma_f32_32x32x16_bf16 v[80:95], v[242:245], v[40:43], v[80:95]
	ds_read_b128 v[40:43], v32 offset:17120
	ds_read_b128 v[242:245], v45 offset:256
	s_waitcnt lgkmcnt(5)
	v_mfma_f32_32x32x16_bf16 v[96:111], v[234:237], v[246:249], v[96:111]
	ds_read_b128 v[246:249], v32 offset:256
	s_waitcnt lgkmcnt(5)
	v_mfma_f32_32x32x16_bf16 v[80:95], v[234:237], v[250:253], v[80:95]
	ds_read_b128 v[250:253], v32 offset:17152
	ds_read_b128 v[234:237], v45 offset:288
	s_waitcnt lgkmcnt(5)
	v_mfma_f32_32x32x16_bf16 v[96:111], v[238:241], v[36:39], v[96:111]
	ds_read_b128 v[36:39], v32 offset:288
	s_waitcnt lgkmcnt(5)
	v_mfma_f32_32x32x16_bf16 v[80:95], v[238:241], v[40:43], v[80:95]
	ds_read_b128 v[40:43], v32 offset:17184
	ds_read_b128 v[238:241], v45 offset:320
	s_waitcnt lgkmcnt(5)
	v_mfma_f32_32x32x16_bf16 v[96:111], v[242:245], v[246:249], v[96:111]
	ds_read_b128 v[246:249], v32 offset:320
	s_waitcnt lgkmcnt(5)
	v_mfma_f32_32x32x16_bf16 v[80:95], v[242:245], v[250:253], v[80:95]
	ds_read_b128 v[250:253], v32 offset:17216
	ds_read_b128 v[242:245], v45 offset:352
	s_waitcnt lgkmcnt(5)
	v_mfma_f32_32x32x16_bf16 v[96:111], v[234:237], v[36:39], v[96:111]
	ds_read_b128 v[36:39], v32 offset:352
	s_waitcnt lgkmcnt(5)
	v_mfma_f32_32x32x16_bf16 v[80:95], v[234:237], v[40:43], v[80:95]
	ds_read_b128 v[40:43], v32 offset:17248
	ds_read_b128 v[234:237], v45 offset:384
	s_waitcnt lgkmcnt(5)
	v_mfma_f32_32x32x16_bf16 v[96:111], v[238:241], v[246:249], v[96:111]
	ds_read_b128 v[246:249], v32 offset:384
	s_waitcnt lgkmcnt(5)
	v_mfma_f32_32x32x16_bf16 v[80:95], v[238:241], v[250:253], v[80:95]
	ds_read_b128 v[250:253], v32 offset:17280
	ds_read_b128 v[238:241], v45 offset:416
	s_waitcnt lgkmcnt(5)
	v_mfma_f32_32x32x16_bf16 v[96:111], v[242:245], v[36:39], v[96:111]
	ds_read_b128 v[36:39], v32 offset:416
	s_waitcnt lgkmcnt(5)
	v_mfma_f32_32x32x16_bf16 v[80:95], v[242:245], v[40:43], v[80:95]
	ds_read_b128 v[40:43], v32 offset:17312
	ds_read_b128 v[242:245], v45 offset:448
	s_waitcnt lgkmcnt(5)
	v_mfma_f32_32x32x16_bf16 v[96:111], v[234:237], v[246:249], v[96:111]
	ds_read_b128 v[246:249], v32 offset:448
	s_waitcnt lgkmcnt(5)
	v_mfma_f32_32x32x16_bf16 v[80:95], v[234:237], v[250:253], v[80:95]
	ds_read_b128 v[250:253], v32 offset:17344
	ds_read_b128 v[234:237], v45 offset:480
	s_waitcnt lgkmcnt(5)
	v_mfma_f32_32x32x16_bf16 v[96:111], v[238:241], v[36:39], v[96:111]
	ds_read_b128 v[36:39], v32 offset:480
	s_waitcnt lgkmcnt(5)
	v_mfma_f32_32x32x16_bf16 v[80:95], v[238:241], v[40:43], v[80:95]
	ds_read_b128 v[40:43], v32 offset:17376
	s_waitcnt lgkmcnt(4)
	v_mfma_f32_32x32x16_bf16 v[96:111], v[242:245], v[246:249], v[96:111]
	s_waitcnt lgkmcnt(3)
	v_mfma_f32_32x32x16_bf16 v[80:95], v[242:245], v[250:253], v[80:95]
	s_waitcnt lgkmcnt(1)
	v_mfma_f32_32x32x16_bf16 v[96:111], v[234:237], v[36:39], v[96:111]
	s_waitcnt lgkmcnt(0)
	v_mfma_f32_32x32x16_bf16 v[80:95], v[234:237], v[40:43], v[80:95]
	s_barrier
	s_nop 15
	ds_write_b128 v165, v[96:99]
	ds_write_b128 v165, v[100:103] offset:32
	ds_write_b128 v165, v[104:107] offset:64
	ds_write_b128 v165, v[108:111] offset:96
	ds_write_b128 v165, v[80:83] offset:16896
	ds_write_b128 v165, v[84:87] offset:16928
	ds_write_b128 v165, v[88:91] offset:16960
	ds_write_b128 v165, v[92:95] offset:16992
	s_waitcnt lgkmcnt(0)
	s_barrier
	s_and_b64 s[30:31], s[10:11], exec
	s_cbranch_scc0 .Ls5_nopf
	v_mov_b32_e32 v34, 0x2000
	v_mov_b32_e32 v35, v33
	v_lshl_add_u64 v[34:35], v[148:149], 0, v[34:35]
	global_load_dwordx4 v[100:103], v[148:149], off offset:-4096
	global_load_dwordx4 v[104:107], v[148:149], off offset:-3072
	global_load_dwordx4 v[108:111], v[148:149], off offset:-2048
	global_load_dwordx4 v[166:169], v[148:149], off offset:-1024
	global_load_dwordx4 v[170:173], v[148:149], off offset:0
	global_load_dwordx4 v[174:177], v[148:149], off offset:1024
	global_load_dwordx4 v[190:193], v[148:149], off offset:2048
	global_load_dwordx4 v[194:197], v[148:149], off offset:3072
	global_load_dwordx4 v[198:201], v[34:35], off offset:-4096
	global_load_dwordx4 v[202:205], v[34:35], off offset:-3072
	global_load_dwordx4 v[206:209], v[34:35], off offset:-2048
	global_load_dwordx4 v[234:237], v[34:35], off offset:-1024
	global_load_dwordx4 v[238:241], v[34:35], off offset:0
	global_load_dwordx4 v[242:245], v[34:35], off offset:1024
	global_load_dwordx4 v[246:249], v[34:35], off offset:2048
	global_load_dwordx4 v[250:253], v[34:35], off offset:3072

.LBB0_724:
	s_lshl_b32 s24, s88, 6
	v_mov_b32_e32 v38, s24
	v_mov_b32_e32 v39, v33
	v_lshl_add_u64 v[38:39], v[152:153], 0, v[38:39]
	global_load_dwordx4 v[100:103], v[38:39], off offset:-4096
	global_load_dwordx4 v[104:107], v[38:39], off offset:-3072
	global_load_dwordx4 v[108:111], v[38:39], off offset:-2048
	global_load_dwordx4 v[166:169], v[38:39], off offset:-1024
	global_load_dwordx4 v[170:173], v[38:39], off
	global_load_dwordx4 v[174:177], v[38:39], off offset:1024
	global_load_dwordx4 v[190:193], v[38:39], off offset:2048
	global_load_dwordx4 v[194:197], v[38:39], off offset:3072
	v_add_u32_e32 v32, 0x10800, v156
	s_waitcnt lgkmcnt(0)
	s_barrier
	ds_read_b128 v[198:201], v32
	ds_read_b128 v[202:205], v32 offset:16
	ds_read_b128 v[206:209], v32 offset:16896
	ds_read_b128 v[234:237], v32 offset:16912
	ds_read_b128 v[238:241], v32 offset:33792
	ds_read_b128 v[242:245], v32 offset:33808
	s_waitcnt vmcnt(7) lgkmcnt(4)
	v_cvt_pk_bf16_f32 v246, v198, v199
	v_cvt_pk_bf16_f32 v247, v200, v201
	v_cvt_pk_bf16_f32 v248, v202, v203
	v_cvt_pk_bf16_f32 v249, v204, v205
	s_nop 1
	v_mfma_f32_32x32x16_bf16 v[64:79], v[100:103], v[246:249], v[64:79]
	ds_read_b128 v[198:201], v32 offset:50688
	ds_read_b128 v[202:205], v32 offset:50704
	s_waitcnt lgkmcnt(4)
	v_cvt_pk_bf16_f32 v250, v206, v207
	v_cvt_pk_bf16_f32 v251, v208, v209
	v_cvt_pk_bf16_f32 v252, v234, v235
	v_cvt_pk_bf16_f32 v253, v236, v237
	s_nop 1
	v_mfma_f32_32x32x16_bf16 v[48:63], v[100:103], v[250:253], v[48:63]
	ds_read_b128 v[206:209], v32 offset:64
	ds_read_b128 v[234:237], v32 offset:80
	s_waitcnt lgkmcnt(4)
	v_cvt_pk_bf16_f32 v246, v238, v239
	v_cvt_pk_bf16_f32 v247, v240, v241
	v_cvt_pk_bf16_f32 v248, v242, v243
	v_cvt_pk_bf16_f32 v249, v244, v245
	s_nop 1
	v_mfma_f32_32x32x16_bf16 v[16:31], v[100:103], v[246:249], v[16:31]
	ds_read_b128 v[238:241], v32 offset:16960
	ds_read_b128 v[242:245], v32 offset:16976
	s_waitcnt lgkmcnt(4)
	v_cvt_pk_bf16_f32 v250, v198, v199
	v_cvt_pk_bf16_f32 v251, v200, v201
	v_cvt_pk_bf16_f32 v252, v202, v203
	v_cvt_pk_bf16_f32 v253, v204, v205
	s_nop 1
	v_mfma_f32_32x32x16_bf16 v[0:15], v[100:103], v[250:253], v[0:15]
	ds_read_b128 v[198:201], v32 offset:33856
	ds_read_b128 v[202:205], v32 offset:33872
	s_waitcnt vmcnt(6) lgkmcnt(4)
	v_cvt_pk_bf16_f32 v246, v206, v207
	v_cvt_pk_bf16_f32 v247, v208, v209
	v_cvt_pk_bf16_f32 v248, v234, v235
	v_cvt_pk_bf16_f32 v249, v236, v237
	s_nop 1
	v_mfma_f32_32x32x16_bf16 v[64:79], v[104:107], v[246:249], v[64:79]
	ds_read_b128 v[206:209], v32 offset:50752
	ds_read_b128 v[234:237], v32 offset:50768
	s_waitcnt lgkmcnt(4)
	v_cvt_pk_bf16_f32 v250, v238, v239
	v_cvt_pk_bf16_f32 v251, v240, v241
	v_cvt_pk_bf16_f32 v252, v242, v243
	v_cvt_pk_bf16_f32 v253, v244, v245
	s_nop 1
	v_mfma_f32_32x32x16_bf16 v[48:63], v[104:107], v[250:253], v[48:63]
	ds_read_b128 v[238:241], v32 offset:128
	ds_read_b128 v[242:245], v32 offset:144
	s_waitcnt lgkmcnt(4)
	v_cvt_pk_bf16_f32 v246, v198, v199
	v_cvt_pk_bf16_f32 v247, v200, v201
	v_cvt_pk_bf16_f32 v248, v202, v203
	v_cvt_pk_bf16_f32 v249, v204, v205
	s_nop 1
	v_mfma_f32_32x32x16_bf16 v[16:31], v[104:107], v[246:249], v[16:31]
	ds_read_b128 v[198:201], v32 offset:17024
	ds_read_b128 v[202:205], v32 offset:17040
	s_waitcnt lgkmcnt(4)
	v_cvt_pk_bf16_f32 v250, v206, v207
	v_cvt_pk_bf16_f32 v251, v208, v209
	v_cvt_pk_bf16_f32 v252, v234, v235
	v_cvt_pk_bf16_f32 v253, v236, v237
	s_nop 1
	v_mfma_f32_32x32x16_bf16 v[0:15], v[104:107], v[250:253], v[0:15]
	ds_read_b128 v[206:209], v32 offset:33920
	ds_read_b128 v[234:237], v32 offset:33936
	s_waitcnt vmcnt(5) lgkmcnt(4)
	v_cvt_pk_bf16_f32 v246, v238, v239
	v_cvt_pk_bf16_f32 v247, v240, v241
	v_cvt_pk_bf16_f32 v248, v242, v243
	v_cvt_pk_bf16_f32 v249, v244, v245
	s_nop 1
	v_mfma_f32_32x32x16_bf16 v[64:79], v[108:111], v[246:249], v[64:79]
	ds_read_b128 v[238:241], v32 offset:50816
	ds_read_b128 v[242:245], v32 offset:50832
	s_waitcnt lgkmcnt(4)
	v_cvt_pk_bf16_f32 v250, v198, v199
	v_cvt_pk_bf16_f32 v251, v200, v201
	v_cvt_pk_bf16_f32 v252, v202, v203
	v_cvt_pk_bf16_f32 v253, v204, v205
	s_nop 1
	v_mfma_f32_32x32x16_bf16 v[48:63], v[108:111], v[250:253], v[48:63]
	ds_read_b128 v[198:201], v32 offset:192
	ds_read_b128 v[202:205], v32 offset:208
	s_waitcnt lgkmcnt(4)
	v_cvt_pk_bf16_f32 v246, v206, v207
	v_cvt_pk_bf16_f32 v247, v208, v209
	v_cvt_pk_bf16_f32 v248, v234, v235
	v_cvt_pk_bf16_f32 v249, v236, v237
	s_nop 1
	v_mfma_f32_32x32x16_bf16 v[16:31], v[108:111], v[246:249], v[16:31]
	ds_read_b128 v[206:209], v32 offset:17088
	ds_read_b128 v[234:237], v32 offset:17104
	s_waitcnt lgkmcnt(4)
	v_cvt_pk_bf16_f32 v250, v238, v239
	v_cvt_pk_bf16_f32 v251, v240, v241
	v_cvt_pk_bf16_f32 v252, v242, v243
	v_cvt_pk_bf16_f32 v253, v244, v245
	s_nop 1
	v_mfma_f32_32x32x16_bf16 v[0:15], v[108:111], v[250:253], v[0:15]
	ds_read_b128 v[238:241], v32 offset:33984
	ds_read_b128 v[242:245], v32 offset:34000
	s_waitcnt vmcnt(4) lgkmcnt(4)
	v_cvt_pk_bf16_f32 v246, v198, v199
	v_cvt_pk_bf16_f32 v247, v200, v201
	v_cvt_pk_bf16_f32 v248, v202, v203
	v_cvt_pk_bf16_f32 v249, v204, v205
	s_nop 1
	v_mfma_f32_32x32x16_bf16 v[64:79], v[166:169], v[246:249], v[64:79]
	ds_read_b128 v[198:201], v32 offset:50880
	ds_read_b128 v[202:205], v32 offset:50896
	s_waitcnt lgkmcnt(4)
	v_cvt_pk_bf16_f32 v250, v206, v207
	v_cvt_pk_bf16_f32 v251, v208, v209
	v_cvt_pk_bf16_f32 v252, v234, v235
	v_cvt_pk_bf16_f32 v253, v236, v237
	s_nop 1
	v_mfma_f32_32x32x16_bf16 v[48:63], v[166:169], v[250:253], v[48:63]
	ds_read_b128 v[206:209], v32 offset:256
	ds_read_b128 v[234:237], v32 offset:272
	s_waitcnt lgkmcnt(4)
	v_cvt_pk_bf16_f32 v246, v238, v239
	v_cvt_pk_bf16_f32 v247, v240, v241
	v_cvt_pk_bf16_f32 v248, v242, v243
	v_cvt_pk_bf16_f32 v249, v244, v245
	s_nop 1
	v_mfma_f32_32x32x16_bf16 v[16:31], v[166:169], v[246:249], v[16:31]
	ds_read_b128 v[238:241], v32 offset:17152
	ds_read_b128 v[242:245], v32 offset:17168
	s_waitcnt lgkmcnt(4)
	v_cvt_pk_bf16_f32 v250, v198, v199
	v_cvt_pk_bf16_f32 v251, v200, v201
	v_cvt_pk_bf16_f32 v252, v202, v203
	v_cvt_pk_bf16_f32 v253, v204, v205
	s_nop 1
	v_mfma_f32_32x32x16_bf16 v[0:15], v[166:169], v[250:253], v[0:15]
	ds_read_b128 v[198:201], v32 offset:34048
	ds_read_b128 v[202:205], v32 offset:34064
	s_waitcnt vmcnt(3) lgkmcnt(4)
	v_cvt_pk_bf16_f32 v246, v206, v207
	v_cvt_pk_bf16_f32 v247, v208, v209
	v_cvt_pk_bf16_f32 v248, v234, v235
	v_cvt_pk_bf16_f32 v249, v236, v237
	s_nop 1
	v_mfma_f32_32x32x16_bf16 v[64:79], v[170:173], v[246:249], v[64:79]
	ds_read_b128 v[206:209], v32 offset:50944
	ds_read_b128 v[234:237], v32 offset:50960
	s_waitcnt lgkmcnt(4)
	v_cvt_pk_bf16_f32 v250, v238, v239
	v_cvt_pk_bf16_f32 v251, v240, v241
	v_cvt_pk_bf16_f32 v252, v242, v243
	v_cvt_pk_bf16_f32 v253, v244, v245
	s_nop 1
	v_mfma_f32_32x32x16_bf16 v[48:63], v[170:173], v[250:253], v[48:63]
	ds_read_b128 v[238:241], v32 offset:320
	ds_read_b128 v[242:245], v32 offset:336
	s_waitcnt lgkmcnt(4)
	v_cvt_pk_bf16_f32 v246, v198, v199
	v_cvt_pk_bf16_f32 v247, v200, v201
	v_cvt_pk_bf16_f32 v248, v202, v203
	v_cvt_pk_bf16_f32 v249, v204, v205
	s_nop 1
	v_mfma_f32_32x32x16_bf16 v[16:31], v[170:173], v[246:249], v[16:31]
	ds_read_b128 v[198:201], v32 offset:17216
	ds_read_b128 v[202:205], v32 offset:17232
	s_waitcnt lgkmcnt(4)
	v_cvt_pk_bf16_f32 v250, v206, v207
	v_cvt_pk_bf16_f32 v251, v208, v209
	v_cvt_pk_bf16_f32 v252, v234, v235
	v_cvt_pk_bf16_f32 v253, v236, v237
	s_nop 1
	v_mfma_f32_32x32x16_bf16 v[0:15], v[170:173], v[250:253], v[0:15]
	ds_read_b128 v[206:209], v32 offset:34112
	ds_read_b128 v[234:237], v32 offset:34128
	s_waitcnt vmcnt(2) lgkmcnt(4)
	v_cvt_pk_bf16_f32 v246, v238, v239
	v_cvt_pk_bf16_f32 v247, v240, v241
	v_cvt_pk_bf16_f32 v248, v242, v243
	v_cvt_pk_bf16_f32 v249, v244, v245
	s_nop 1
	v_mfma_f32_32x32x16_bf16 v[64:79], v[174:177], v[246:249], v[64:79]
	ds_read_b128 v[238:241], v32 offset:51008
	ds_read_b128 v[242:245], v32 offset:51024
	s_waitcnt lgkmcnt(4)
	v_cvt_pk_bf16_f32 v250, v198, v199
	v_cvt_pk_bf16_f32 v251, v200, v201
	v_cvt_pk_bf16_f32 v252, v202, v203
	v_cvt_pk_bf16_f32 v253, v204, v205
	s_nop 1
	v_mfma_f32_32x32x16_bf16 v[48:63], v[174:177], v[250:253], v[48:63]
	ds_read_b128 v[198:201], v32 offset:384
	ds_read_b128 v[202:205], v32 offset:400
	s_waitcnt lgkmcnt(4)
	v_cvt_pk_bf16_f32 v246, v206, v207
	v_cvt_pk_bf16_f32 v247, v208, v209
	v_cvt_pk_bf16_f32 v248, v234, v235
	v_cvt_pk_bf16_f32 v249, v236, v237
	s_nop 1
	v_mfma_f32_32x32x16_bf16 v[16:31], v[174:177], v[246:249], v[16:31]
	ds_read_b128 v[206:209], v32 offset:17280
	ds_read_b128 v[234:237], v32 offset:17296
	s_waitcnt lgkmcnt(4)
	v_cvt_pk_bf16_f32 v250, v238, v239
	v_cvt_pk_bf16_f32 v251, v240, v241
	v_cvt_pk_bf16_f32 v252, v242, v243
	v_cvt_pk_bf16_f32 v253, v244, v245
	s_nop 1
	v_mfma_f32_32x32x16_bf16 v[0:15], v[174:177], v[250:253], v[0:15]
	ds_read_b128 v[238:241], v32 offset:34176
	ds_read_b128 v[242:245], v32 offset:34192
	s_waitcnt vmcnt(1) lgkmcnt(4)
	v_cvt_pk_bf16_f32 v246, v198, v199
	v_cvt_pk_bf16_f32 v247, v200, v201
	v_cvt_pk_bf16_f32 v248, v202, v203
	v_cvt_pk_bf16_f32 v249, v204, v205
	s_nop 1
	v_mfma_f32_32x32x16_bf16 v[64:79], v[190:193], v[246:249], v[64:79]
	ds_read_b128 v[198:201], v32 offset:51072
	ds_read_b128 v[202:205], v32 offset:51088
	s_waitcnt lgkmcnt(4)
	v_cvt_pk_bf16_f32 v250, v206, v207
	v_cvt_pk_bf16_f32 v251, v208, v209
	v_cvt_pk_bf16_f32 v252, v234, v235
	v_cvt_pk_bf16_f32 v253, v236, v237
	s_nop 1
	v_mfma_f32_32x32x16_bf16 v[48:63], v[190:193], v[250:253], v[48:63]
	ds_read_b128 v[206:209], v32 offset:448
	ds_read_b128 v[234:237], v32 offset:464
	s_waitcnt lgkmcnt(4)
	v_cvt_pk_bf16_f32 v246, v238, v239
	v_cvt_pk_bf16_f32 v247, v240, v241
	v_cvt_pk_bf16_f32 v248, v242, v243
	v_cvt_pk_bf16_f32 v249, v244, v245
	s_nop 1
	v_mfma_f32_32x32x16_bf16 v[16:31], v[190:193], v[246:249], v[16:31]
	ds_read_b128 v[238:241], v32 offset:17344
	ds_read_b128 v[242:245], v32 offset:17360
	s_waitcnt lgkmcnt(4)
	v_cvt_pk_bf16_f32 v250, v198, v199
	v_cvt_pk_bf16_f32 v251, v200, v201
	v_cvt_pk_bf16_f32 v252, v202, v203
	v_cvt_pk_bf16_f32 v253, v204, v205
	s_nop 1
	v_mfma_f32_32x32x16_bf16 v[0:15], v[190:193], v[250:253], v[0:15]
	ds_read_b128 v[198:201], v32 offset:34240
	ds_read_b128 v[202:205], v32 offset:34256
	s_waitcnt vmcnt(0) lgkmcnt(4)
	v_cvt_pk_bf16_f32 v246, v206, v207
	v_cvt_pk_bf16_f32 v247, v208, v209
	v_cvt_pk_bf16_f32 v248, v234, v235
	v_cvt_pk_bf16_f32 v249, v236, v237
	s_nop 1
	v_mfma_f32_32x32x16_bf16 v[64:79], v[194:197], v[246:249], v[64:79]
	ds_read_b128 v[206:209], v32 offset:51136
	ds_read_b128 v[234:237], v32 offset:51152
	s_waitcnt lgkmcnt(4)
	v_cvt_pk_bf16_f32 v250, v238, v239
	v_cvt_pk_bf16_f32 v251, v240, v241
	v_cvt_pk_bf16_f32 v252, v242, v243
	v_cvt_pk_bf16_f32 v253, v244, v245
	s_nop 1
	v_mfma_f32_32x32x16_bf16 v[48:63], v[194:197], v[250:253], v[48:63]
	s_waitcnt lgkmcnt(2)
	v_cvt_pk_bf16_f32 v246, v198, v199
	v_cvt_pk_bf16_f32 v247, v200, v201
	v_cvt_pk_bf16_f32 v248, v202, v203
	v_cvt_pk_bf16_f32 v249, v204, v205
	s_nop 1
	v_mfma_f32_32x32x16_bf16 v[16:31], v[194:197], v[246:249], v[16:31]
	s_waitcnt lgkmcnt(0)
	v_cvt_pk_bf16_f32 v250, v206, v207
	v_cvt_pk_bf16_f32 v251, v208, v209
	v_cvt_pk_bf16_f32 v252, v234, v235
	v_cvt_pk_bf16_f32 v253, v236, v237
	s_nop 1
	v_mfma_f32_32x32x16_bf16 v[0:15], v[194:197], v[250:253], v[0:15]
	s_movk_i32 s88, 0x80
	s_mov_b64 s[10:11], 0
	s_and_b64 vcc, exec, s[8:9]
	s_barrier
	s_cbranch_vccz .LBB0_719
	v_mul_f32_e32 v32, 0x3d372713, v64
	v_mul_f32_e32 v32, v64, v32
	v_fma_f32 v32, v64, v32, v64
	v_mul_f32_e32 v32, 0x3f4c422a, v32
	v_add_f32_e32 v32, v32, v32
	v_mul_f32_e32 v32, 0x3fb8aa3b, v32
	v_exp_f32_e32 v32, v32
	v_mul_f32_e32 v38, 0.5, v64
	v_mul_f32_e32 v39, 0.5, v65
	v_mul_f32_e32 v40, 0.5, v67
	v_add_f32_e32 v32, 1.0, v32
	v_rcp_f32_e32 v32, v32
	s_ashr_i32 s8, s6, 5
	s_ashr_i32 s9, s8, 31
	s_lshl_b64 s[10:11], s[8:9], 11
	v_fma_f32 v32, v32, -2.0, 1.0
	v_add_f32_e32 v32, 1.0, v32
	v_mul_f32_e32 v32, v38, v32
	v_mul_f32_e32 v38, 0x3d372713, v65
	v_mul_f32_e32 v38, v65, v38
	v_fma_f32 v38, v65, v38, v65
	v_mul_f32_e32 v38, 0x3f4c422a, v38
	v_add_f32_e32 v38, v38, v38
	v_mul_f32_e32 v38, 0x3fb8aa3b, v38
	v_exp_f32_e32 v38, v38
	s_lshl_b32 s7, s23, 5
	v_mov_b32_e32 v35, s11
	v_or_b32_e32 v34, s10, v118
	v_add_f32_e32 v38, 1.0, v38
	v_rcp_f32_e32 v38, v38
	s_add_u32 s8, s14, s7
	v_lshl_add_u64 v[36:37], v[34:35], 0, v[114:115]
	s_addc_u32 s9, s15, 0
	v_fma_f32 v38, v38, -2.0, 1.0
	v_add_f32_e32 v38, 1.0, v38
	v_mul_f32_e32 v38, v39, v38
	v_cvt_pk_bf16_f32 v38, v32, v38
	v_mul_f32_e32 v32, 0x3d372713, v66
	v_mul_f32_e32 v32, v66, v32
	v_fma_f32 v32, v66, v32, v66
	v_mul_f32_e32 v32, 0x3f4c422a, v32
	v_add_f32_e32 v32, v32, v32
	v_mul_f32_e32 v32, 0x3fb8aa3b, v32
	v_exp_f32_e32 v32, v32
	v_mul_f32_e32 v39, 0.5, v66
	v_lshlrev_b64 v[36:37], 10, v[36:37]
	v_lshl_add_u64 v[36:37], s[8:9], 0, v[36:37]
	v_add_f32_e32 v32, 1.0, v32
	v_rcp_f32_e32 v32, v32
	v_mov_b32_e32 v147, v33
	v_lshl_add_u64 v[36:37], v[36:37], 0, v[146:147]
	v_lshl_add_u64 v[34:35], v[34:35], 0, v[136:137]
	v_fma_f32 v32, v32, -2.0, 1.0
	v_add_f32_e32 v32, 1.0, v32
	v_mul_f32_e32 v32, v39, v32
	v_mul_f32_e32 v39, 0x3d372713, v67
	v_mul_f32_e32 v39, v67, v39
	v_fma_f32 v39, v67, v39, v67
	v_mul_f32_e32 v39, 0x3f4c422a, v39
	v_add_f32_e32 v39, v39, v39
	v_mul_f32_e32 v39, 0x3fb8aa3b, v39
	v_exp_f32_e32 v39, v39
	v_lshlrev_b64 v[34:35], 10, v[34:35]
	v_lshl_add_u64 v[34:35], s[8:9], 0, v[34:35]
	v_lshl_add_u64 v[34:35], v[34:35], 0, v[146:147]
	v_add_f32_e32 v39, 1.0, v39
	v_rcp_f32_e32 v39, v39
	s_add_i32 s6, s6, s28
	s_add_i32 s17, s17, s28
	s_cmpk_gt_i32 s6, 0x1ff
	v_fma_f32 v39, v39, -2.0, 1.0
	v_add_f32_e32 v39, 1.0, v39
	v_mul_f32_e32 v39, v40, v39
	v_cvt_pk_bf16_f32 v39, v32, v39
	v_mul_f32_e32 v32, 0x3d372713, v68
	v_mul_f32_e32 v32, v68, v32
	v_fma_f32 v32, v68, v32, v68
	v_mul_f32_e32 v32, 0x3f4c422a, v32
	v_add_f32_e32 v32, v32, v32
	v_mul_f32_e32 v32, 0x3fb8aa3b, v32
	v_exp_f32_e32 v32, v32
	global_store_dwordx2 v[36:37], v[38:39], off
	v_mul_f32_e32 v38, 0.5, v68
	v_mul_f32_e32 v39, 0.5, v69
	v_add_f32_e32 v32, 1.0, v32
	v_rcp_f32_e32 v32, v32
	v_mul_f32_e32 v40, 0.5, v71
	v_fma_f32 v32, v32, -2.0, 1.0
	v_add_f32_e32 v32, 1.0, v32
	v_mul_f32_e32 v32, v38, v32
	v_mul_f32_e32 v38, 0x3d372713, v69
	v_mul_f32_e32 v38, v69, v38
	v_fma_f32 v38, v69, v38, v69
	v_mul_f32_e32 v38, 0x3f4c422a, v38
	v_add_f32_e32 v38, v38, v38
	v_mul_f32_e32 v38, 0x3fb8aa3b, v38
	v_exp_f32_e32 v38, v38
	s_nop 0
	v_add_f32_e32 v38, 1.0, v38
	v_rcp_f32_e32 v38, v38
	s_nop 0
	v_fma_f32 v38, v38, -2.0, 1.0
	v_add_f32_e32 v38, 1.0, v38
	v_mul_f32_e32 v38, v39, v38
	v_cvt_pk_bf16_f32 v38, v32, v38
	v_mul_f32_e32 v32, 0x3d372713, v70
	v_mul_f32_e32 v32, v70, v32
	v_fma_f32 v32, v70, v32, v70
	v_mul_f32_e32 v32, 0x3f4c422a, v32
	v_add_f32_e32 v32, v32, v32
	v_mul_f32_e32 v32, 0x3fb8aa3b, v32
	v_exp_f32_e32 v32, v32
	v_mul_f32_e32 v39, 0.5, v70
	v_add_f32_e32 v32, 1.0, v32
	v_rcp_f32_e32 v32, v32
	s_nop 0
	v_fma_f32 v32, v32, -2.0, 1.0
	v_add_f32_e32 v32, 1.0, v32
	v_mul_f32_e32 v32, v39, v32
	v_mul_f32_e32 v39, 0x3d372713, v71
	v_mul_f32_e32 v39, v71, v39
	v_fma_f32 v39, v71, v39, v71
	v_mul_f32_e32 v39, 0x3f4c422a, v39
	v_add_f32_e32 v39, v39, v39
	v_mul_f32_e32 v39, 0x3fb8aa3b, v39
	v_exp_f32_e32 v39, v39
	s_nop 0
	v_add_f32_e32 v39, 1.0, v39
	v_rcp_f32_e32 v39, v39
	s_nop 0
	v_fma_f32 v39, v39, -2.0, 1.0
	v_add_f32_e32 v39, 1.0, v39
	v_mul_f32_e32 v39, v40, v39
	v_cvt_pk_bf16_f32 v39, v32, v39
	v_mul_f32_e32 v32, 0x3d372713, v72
	v_mul_f32_e32 v32, v72, v32
	v_fma_f32 v32, v72, v32, v72
	v_mul_f32_e32 v32, 0x3f4c422a, v32
	v_add_f32_e32 v32, v32, v32
	v_mul_f32_e32 v32, 0x3fb8aa3b, v32
	v_exp_f32_e32 v32, v32
	global_store_dwordx2 v[36:37], v[38:39], off offset:16
	v_mul_f32_e32 v36, 0.5, v72
	v_mul_f32_e32 v37, 0.5, v73
	v_add_f32_e32 v32, 1.0, v32
	v_rcp_f32_e32 v32, v32
	v_mul_f32_e32 v38, 0.5, v75
	v_mul_f32_e32 v39, 0.5, v49
	v_mul_f32_e32 v40, 0.5, v51
	v_fma_f32 v32, v32, -2.0, 1.0
	v_add_f32_e32 v32, 1.0, v32
	v_mul_f32_e32 v32, v36, v32
	v_mul_f32_e32 v36, 0x3d372713, v73
	v_mul_f32_e32 v36, v73, v36
	v_fma_f32 v36, v73, v36, v73
	v_mul_f32_e32 v36, 0x3f4c422a, v36
	v_add_f32_e32 v36, v36, v36
	v_mul_f32_e32 v36, 0x3fb8aa3b, v36
	v_exp_f32_e32 v36, v36
	s_nop 0
	v_add_f32_e32 v36, 1.0, v36
	v_rcp_f32_e32 v36, v36
	s_nop 0
	v_fma_f32 v36, v36, -2.0, 1.0
	v_add_f32_e32 v36, 1.0, v36
	v_mul_f32_e32 v36, v37, v36
	v_cvt_pk_bf16_f32 v36, v32, v36
	v_mul_f32_e32 v32, 0x3d372713, v74
	v_mul_f32_e32 v32, v74, v32
	v_fma_f32 v32, v74, v32, v74
	v_mul_f32_e32 v32, 0x3f4c422a, v32
	v_add_f32_e32 v32, v32, v32
	v_mul_f32_e32 v32, 0x3fb8aa3b, v32
	v_exp_f32_e32 v32, v32
	v_mul_f32_e32 v37, 0.5, v74
	v_add_f32_e32 v32, 1.0, v32
	v_rcp_f32_e32 v32, v32
	s_nop 0
	v_fma_f32 v32, v32, -2.0, 1.0
	v_add_f32_e32 v32, 1.0, v32
	v_mul_f32_e32 v32, v37, v32
	v_mul_f32_e32 v37, 0x3d372713, v75
	v_mul_f32_e32 v37, v75, v37
	v_fma_f32 v37, v75, v37, v75
	v_mul_f32_e32 v37, 0x3f4c422a, v37
	v_add_f32_e32 v37, v37, v37
	v_mul_f32_e32 v37, 0x3fb8aa3b, v37
	v_exp_f32_e32 v37, v37
	s_nop 0
	v_add_f32_e32 v37, 1.0, v37
	v_rcp_f32_e32 v37, v37
	s_nop 0
	v_fma_f32 v37, v37, -2.0, 1.0
	v_add_f32_e32 v37, 1.0, v37
	v_mul_f32_e32 v37, v38, v37
	v_cvt_pk_bf16_f32 v37, v32, v37
	v_mul_f32_e32 v32, 0x3d372713, v76
	v_mul_f32_e32 v32, v76, v32
	v_fma_f32 v32, v76, v32, v76
	v_mul_f32_e32 v32, 0x3f4c422a, v32
	v_add_f32_e32 v32, v32, v32
	v_mul_f32_e32 v32, 0x3fb8aa3b, v32
	v_exp_f32_e32 v32, v32
	global_store_dwordx2 v[34:35], v[36:37], off
	v_mul_f32_e32 v36, 0.5, v76
	v_mul_f32_e32 v37, 0.5, v77
	v_add_f32_e32 v32, 1.0, v32
	v_rcp_f32_e32 v32, v32
	v_mul_f32_e32 v38, 0.5, v79
	v_fma_f32 v32, v32, -2.0, 1.0
	v_add_f32_e32 v32, 1.0, v32
	v_mul_f32_e32 v32, v36, v32
	v_mul_f32_e32 v36, 0x3d372713, v77
	v_mul_f32_e32 v36, v77, v36
	v_fma_f32 v36, v77, v36, v77
	v_mul_f32_e32 v36, 0x3f4c422a, v36
	v_add_f32_e32 v36, v36, v36
	v_mul_f32_e32 v36, 0x3fb8aa3b, v36
	v_exp_f32_e32 v36, v36
	s_nop 0
	v_add_f32_e32 v36, 1.0, v36
	v_rcp_f32_e32 v36, v36
	s_nop 0
	v_fma_f32 v36, v36, -2.0, 1.0
	v_add_f32_e32 v36, 1.0, v36
	v_mul_f32_e32 v36, v37, v36
	v_cvt_pk_bf16_f32 v36, v32, v36
	v_mul_f32_e32 v32, 0x3d372713, v78
	v_mul_f32_e32 v32, v78, v32
	v_fma_f32 v32, v78, v32, v78
	v_mul_f32_e32 v32, 0x3f4c422a, v32
	v_add_f32_e32 v32, v32, v32
	v_mul_f32_e32 v32, 0x3fb8aa3b, v32
	v_exp_f32_e32 v32, v32
	v_mul_f32_e32 v37, 0.5, v78
	v_add_f32_e32 v32, 1.0, v32
	v_rcp_f32_e32 v32, v32
	s_nop 0
	v_fma_f32 v32, v32, -2.0, 1.0
	v_add_f32_e32 v32, 1.0, v32
	v_mul_f32_e32 v32, v37, v32
	v_mul_f32_e32 v37, 0x3d372713, v79
	v_mul_f32_e32 v37, v79, v37
	v_fma_f32 v37, v79, v37, v79
	v_mul_f32_e32 v37, 0x3f4c422a, v37
	v_add_f32_e32 v37, v37, v37
	v_mul_f32_e32 v37, 0x3fb8aa3b, v37
	v_exp_f32_e32 v37, v37
	s_nop 0
	v_add_f32_e32 v37, 1.0, v37
	v_rcp_f32_e32 v37, v37
	s_nop 0
	v_fma_f32 v37, v37, -2.0, 1.0
	v_add_f32_e32 v37, 1.0, v37
	v_mul_f32_e32 v37, v38, v37
	v_cvt_pk_bf16_f32 v37, v32, v37
	v_mul_f32_e32 v32, 0x3d372713, v48
	v_mul_f32_e32 v32, v48, v32
	v_fma_f32 v32, v48, v32, v48
	v_mul_f32_e32 v32, 0x3f4c422a, v32
	v_add_f32_e32 v32, v32, v32
	v_mul_f32_e32 v32, 0x3fb8aa3b, v32
	v_exp_f32_e32 v32, v32
	v_mul_f32_e32 v38, 0.5, v48
	global_store_dwordx2 v[34:35], v[36:37], off offset:16
	v_mov_b32_e32 v35, s11
	v_add_f32_e32 v32, 1.0, v32
	v_rcp_f32_e32 v32, v32
	v_or_b32_e32 v34, s10, v138
	v_lshl_add_u64 v[36:37], v[34:35], 0, v[114:115]
	v_lshlrev_b64 v[36:37], 10, v[36:37]
	v_fma_f32 v32, v32, -2.0, 1.0
	v_add_f32_e32 v32, 1.0, v32
	v_mul_f32_e32 v32, v38, v32
	v_mul_f32_e32 v38, 0x3d372713, v49
	v_mul_f32_e32 v38, v49, v38
	v_fma_f32 v38, v49, v38, v49
	v_mul_f32_e32 v38, 0x3f4c422a, v38
	v_add_f32_e32 v38, v38, v38
	v_mul_f32_e32 v38, 0x3fb8aa3b, v38
	v_exp_f32_e32 v38, v38
	v_lshl_add_u64 v[36:37], s[8:9], 0, v[36:37]
	v_lshl_add_u64 v[36:37], v[36:37], 0, v[146:147]
	v_lshl_add_u64 v[34:35], v[34:35], 0, v[136:137]
	v_add_f32_e32 v38, 1.0, v38
	v_rcp_f32_e32 v38, v38
	v_lshlrev_b64 v[34:35], 10, v[34:35]
	v_lshl_add_u64 v[34:35], s[8:9], 0, v[34:35]
	v_lshl_add_u64 v[34:35], v[34:35], 0, v[146:147]
	v_fma_f32 v38, v38, -2.0, 1.0
	v_add_f32_e32 v38, 1.0, v38
	v_mul_f32_e32 v38, v39, v38
	v_cvt_pk_bf16_f32 v38, v32, v38
	v_mul_f32_e32 v32, 0x3d372713, v50
	v_mul_f32_e32 v32, v50, v32
	v_fma_f32 v32, v50, v32, v50
	v_mul_f32_e32 v32, 0x3f4c422a, v32
	v_add_f32_e32 v32, v32, v32
	v_mul_f32_e32 v32, 0x3fb8aa3b, v32
	v_exp_f32_e32 v32, v32
	v_mul_f32_e32 v39, 0.5, v50
	v_add_f32_e32 v32, 1.0, v32
	v_rcp_f32_e32 v32, v32
	s_nop 0
	v_fma_f32 v32, v32, -2.0, 1.0
	v_add_f32_e32 v32, 1.0, v32
	v_mul_f32_e32 v32, v39, v32
	v_mul_f32_e32 v39, 0x3d372713, v51
	v_mul_f32_e32 v39, v51, v39
	v_fma_f32 v39, v51, v39, v51
	v_mul_f32_e32 v39, 0x3f4c422a, v39
	v_add_f32_e32 v39, v39, v39
	v_mul_f32_e32 v39, 0x3fb8aa3b, v39
	v_exp_f32_e32 v39, v39
	s_nop 0
	v_add_f32_e32 v39, 1.0, v39
	v_rcp_f32_e32 v39, v39
	s_nop 0
	v_fma_f32 v39, v39, -2.0, 1.0
	v_add_f32_e32 v39, 1.0, v39
	v_mul_f32_e32 v39, v40, v39
	v_cvt_pk_bf16_f32 v39, v32, v39
	v_mul_f32_e32 v32, 0x3d372713, v52
	v_mul_f32_e32 v32, v52, v32
	v_fma_f32 v32, v52, v32, v52
	v_mul_f32_e32 v32, 0x3f4c422a, v32
	v_add_f32_e32 v32, v32, v32
	v_mul_f32_e32 v32, 0x3fb8aa3b, v32
	v_exp_f32_e32 v32, v32
	global_store_dwordx2 v[36:37], v[38:39], off
	v_mul_f32_e32 v38, 0.5, v52
	v_mul_f32_e32 v39, 0.5, v53
	v_add_f32_e32 v32, 1.0, v32
	v_rcp_f32_e32 v32, v32
	v_mul_f32_e32 v40, 0.5, v55
	v_fma_f32 v32, v32, -2.0, 1.0
	v_add_f32_e32 v32, 1.0, v32
	v_mul_f32_e32 v32, v38, v32
	v_mul_f32_e32 v38, 0x3d372713, v53
	v_mul_f32_e32 v38, v53, v38
	v_fma_f32 v38, v53, v38, v53
	v_mul_f32_e32 v38, 0x3f4c422a, v38
	v_add_f32_e32 v38, v38, v38
	v_mul_f32_e32 v38, 0x3fb8aa3b, v38
	v_exp_f32_e32 v38, v38
	s_nop 0
	v_add_f32_e32 v38, 1.0, v38
	v_rcp_f32_e32 v38, v38
	s_nop 0
	v_fma_f32 v38, v38, -2.0, 1.0
	v_add_f32_e32 v38, 1.0, v38
	v_mul_f32_e32 v38, v39, v38
	v_cvt_pk_bf16_f32 v38, v32, v38
	v_mul_f32_e32 v32, 0x3d372713, v54
	v_mul_f32_e32 v32, v54, v32
	v_fma_f32 v32, v54, v32, v54
	v_mul_f32_e32 v32, 0x3f4c422a, v32
	v_add_f32_e32 v32, v32, v32
	v_mul_f32_e32 v32, 0x3fb8aa3b, v32
	v_exp_f32_e32 v32, v32
	v_mul_f32_e32 v39, 0.5, v54
	v_add_f32_e32 v32, 1.0, v32
	v_rcp_f32_e32 v32, v32
	s_nop 0
	v_fma_f32 v32, v32, -2.0, 1.0
	v_add_f32_e32 v32, 1.0, v32
	v_mul_f32_e32 v32, v39, v32
	v_mul_f32_e32 v39, 0x3d372713, v55
	v_mul_f32_e32 v39, v55, v39
	v_fma_f32 v39, v55, v39, v55
	v_mul_f32_e32 v39, 0x3f4c422a, v39
	v_add_f32_e32 v39, v39, v39
	v_mul_f32_e32 v39, 0x3fb8aa3b, v39
	v_exp_f32_e32 v39, v39
	s_nop 0
	v_add_f32_e32 v39, 1.0, v39
	v_rcp_f32_e32 v39, v39
	s_nop 0
	v_fma_f32 v39, v39, -2.0, 1.0
	v_add_f32_e32 v39, 1.0, v39
	v_mul_f32_e32 v39, v40, v39
	v_cvt_pk_bf16_f32 v39, v32, v39
	v_mul_f32_e32 v32, 0x3d372713, v56
	v_mul_f32_e32 v32, v56, v32
	v_fma_f32 v32, v56, v32, v56
	v_mul_f32_e32 v32, 0x3f4c422a, v32
	v_add_f32_e32 v32, v32, v32
	v_mul_f32_e32 v32, 0x3fb8aa3b, v32
	v_exp_f32_e32 v32, v32
	global_store_dwordx2 v[36:37], v[38:39], off offset:16
	v_mul_f32_e32 v36, 0.5, v56
	v_mul_f32_e32 v37, 0.5, v57
	v_add_f32_e32 v32, 1.0, v32
	v_rcp_f32_e32 v32, v32
	v_mul_f32_e32 v38, 0.5, v59
	v_fma_f32 v32, v32, -2.0, 1.0
	v_add_f32_e32 v32, 1.0, v32
	v_mul_f32_e32 v32, v36, v32
	v_mul_f32_e32 v36, 0x3d372713, v57
	v_mul_f32_e32 v36, v57, v36
	v_fma_f32 v36, v57, v36, v57
	v_mul_f32_e32 v36, 0x3f4c422a, v36
	v_add_f32_e32 v36, v36, v36
	v_mul_f32_e32 v36, 0x3fb8aa3b, v36
	v_exp_f32_e32 v36, v36
	s_nop 0
	v_add_f32_e32 v36, 1.0, v36
	v_rcp_f32_e32 v36, v36
	s_nop 0
	v_fma_f32 v36, v36, -2.0, 1.0
	v_add_f32_e32 v36, 1.0, v36
	v_mul_f32_e32 v36, v37, v36
	v_cvt_pk_bf16_f32 v36, v32, v36
	v_mul_f32_e32 v32, 0x3d372713, v58
	v_mul_f32_e32 v32, v58, v32
	v_fma_f32 v32, v58, v32, v58
	v_mul_f32_e32 v32, 0x3f4c422a, v32
	v_add_f32_e32 v32, v32, v32
	v_mul_f32_e32 v32, 0x3fb8aa3b, v32
	v_exp_f32_e32 v32, v32
	v_mul_f32_e32 v37, 0.5, v58
	v_add_f32_e32 v32, 1.0, v32
	v_rcp_f32_e32 v32, v32
	s_nop 0
	v_fma_f32 v32, v32, -2.0, 1.0
	v_add_f32_e32 v32, 1.0, v32
	v_mul_f32_e32 v32, v37, v32
	v_mul_f32_e32 v37, 0x3d372713, v59
	v_mul_f32_e32 v37, v59, v37
	v_fma_f32 v37, v59, v37, v59
	v_mul_f32_e32 v37, 0x3f4c422a, v37
	v_add_f32_e32 v37, v37, v37
	v_mul_f32_e32 v37, 0x3fb8aa3b, v37
	v_exp_f32_e32 v37, v37
	s_nop 0
	v_add_f32_e32 v37, 1.0, v37
	v_rcp_f32_e32 v37, v37
	s_nop 0
	v_fma_f32 v37, v37, -2.0, 1.0
	v_add_f32_e32 v37, 1.0, v37
	v_mul_f32_e32 v37, v38, v37
	v_cvt_pk_bf16_f32 v37, v32, v37
	v_mul_f32_e32 v32, 0x3d372713, v60
	v_mul_f32_e32 v32, v60, v32
	v_fma_f32 v32, v60, v32, v60
	v_mul_f32_e32 v32, 0x3f4c422a, v32
	v_add_f32_e32 v32, v32, v32
	v_mul_f32_e32 v32, 0x3fb8aa3b, v32
	v_exp_f32_e32 v32, v32
	global_store_dwordx2 v[34:35], v[36:37], off
	v_mul_f32_e32 v36, 0.5, v60
	v_mul_f32_e32 v37, 0.5, v61
	v_add_f32_e32 v32, 1.0, v32
	v_rcp_f32_e32 v32, v32
	v_mul_f32_e32 v38, 0.5, v63
	v_fma_f32 v32, v32, -2.0, 1.0
	v_add_f32_e32 v32, 1.0, v32
	v_mul_f32_e32 v32, v36, v32
	v_mul_f32_e32 v36, 0x3d372713, v61
	v_mul_f32_e32 v36, v61, v36
	v_fma_f32 v36, v61, v36, v61
	v_mul_f32_e32 v36, 0x3f4c422a, v36
	v_add_f32_e32 v36, v36, v36
	v_mul_f32_e32 v36, 0x3fb8aa3b, v36
	v_exp_f32_e32 v36, v36
	s_nop 0
	v_add_f32_e32 v36, 1.0, v36
	v_rcp_f32_e32 v36, v36
	s_nop 0
	v_fma_f32 v36, v36, -2.0, 1.0
	v_add_f32_e32 v36, 1.0, v36
	v_mul_f32_e32 v36, v37, v36
	v_cvt_pk_bf16_f32 v36, v32, v36
	v_mul_f32_e32 v32, 0x3d372713, v62
	v_mul_f32_e32 v32, v62, v32
	v_fma_f32 v32, v62, v32, v62
	v_mul_f32_e32 v32, 0x3f4c422a, v32
	v_add_f32_e32 v32, v32, v32
	v_mul_f32_e32 v32, 0x3fb8aa3b, v32
	v_exp_f32_e32 v32, v32
	v_mul_f32_e32 v37, 0.5, v62
	v_add_f32_e32 v32, 1.0, v32
	v_rcp_f32_e32 v32, v32
	s_nop 0
	v_fma_f32 v32, v32, -2.0, 1.0
	v_add_f32_e32 v32, 1.0, v32
	v_mul_f32_e32 v32, v37, v32
	v_mul_f32_e32 v37, 0x3d372713, v63
	v_mul_f32_e32 v37, v63, v37
	v_fma_f32 v37, v63, v37, v63
	v_mul_f32_e32 v37, 0x3f4c422a, v37
	v_add_f32_e32 v37, v37, v37
	v_mul_f32_e32 v37, 0x3fb8aa3b, v37
	v_exp_f32_e32 v37, v37
	s_nop 0
	v_add_f32_e32 v37, 1.0, v37
	v_rcp_f32_e32 v37, v37
	s_nop 0
	v_fma_f32 v37, v37, -2.0, 1.0
	v_add_f32_e32 v37, 1.0, v37
	v_mul_f32_e32 v37, v38, v37
	v_cvt_pk_bf16_f32 v37, v32, v37
	v_mul_f32_e32 v32, 0x3d372713, v16
	v_mul_f32_e32 v32, v16, v32
	v_fma_f32 v32, v16, v32, v16
	v_mul_f32_e32 v32, 0x3f4c422a, v32
	v_add_f32_e32 v32, v32, v32
	v_mul_f32_e32 v32, 0x3fb8aa3b, v32
	v_exp_f32_e32 v32, v32
	v_mul_f32_e32 v16, 0.5, v16
	global_store_dwordx2 v[34:35], v[36:37], off offset:16
	v_mov_b32_e32 v35, s11
	v_add_f32_e32 v32, 1.0, v32
	v_rcp_f32_e32 v32, v32
	v_or_b32_e32 v34, s10, v140
	v_lshl_add_u64 v[36:37], v[34:35], 0, v[114:115]
	v_fma_f32 v32, v32, -2.0, 1.0
	v_add_f32_e32 v32, 1.0, v32
	v_mul_f32_e32 v16, v16, v32
	v_mul_f32_e32 v32, 0x3d372713, v17
	v_mul_f32_e32 v32, v17, v32
	v_fma_f32 v32, v17, v32, v17
	v_mul_f32_e32 v32, 0x3f4c422a, v32
	v_add_f32_e32 v32, v32, v32
	v_mul_f32_e32 v32, 0x3fb8aa3b, v32
	v_exp_f32_e32 v32, v32
	v_mul_f32_e32 v17, 0.5, v17
	v_add_f32_e32 v32, 1.0, v32
	v_rcp_f32_e32 v32, v32
	s_nop 0
	v_fma_f32 v32, v32, -2.0, 1.0
	v_add_f32_e32 v32, 1.0, v32
	v_mul_f32_e32 v17, v17, v32
	v_cvt_pk_bf16_f32 v16, v16, v17
	v_mul_f32_e32 v17, 0x3d372713, v18
	v_mul_f32_e32 v17, v18, v17
	v_fma_f32 v17, v18, v17, v18
	v_mul_f32_e32 v17, 0x3f4c422a, v17
	v_add_f32_e32 v17, v17, v17
	v_mul_f32_e32 v17, 0x3fb8aa3b, v17
	v_exp_f32_e32 v17, v17
	v_mul_f32_e32 v18, 0.5, v18
	v_add_f32_e32 v17, 1.0, v17
	v_rcp_f32_e32 v17, v17
	s_nop 0
	v_fma_f32 v17, v17, -2.0, 1.0
	v_add_f32_e32 v17, 1.0, v17
	v_mul_f32_e32 v17, v18, v17
	v_mul_f32_e32 v18, 0x3d372713, v19
	v_mul_f32_e32 v18, v19, v18
	v_fma_f32 v18, v19, v18, v19
	v_mul_f32_e32 v18, 0x3f4c422a, v18
	v_add_f32_e32 v18, v18, v18
	v_mul_f32_e32 v18, 0x3fb8aa3b, v18
	v_exp_f32_e32 v18, v18
	v_mul_f32_e32 v19, 0.5, v19
	v_add_f32_e32 v18, 1.0, v18
	v_rcp_f32_e32 v18, v18
	s_nop 0
	v_fma_f32 v18, v18, -2.0, 1.0
	v_add_f32_e32 v18, 1.0, v18
	v_mul_f32_e32 v18, v19, v18
	v_cvt_pk_bf16_f32 v17, v17, v18
	v_lshlrev_b64 v[18:19], 10, v[36:37]
	v_lshl_add_u64 v[18:19], s[8:9], 0, v[18:19]
	v_lshl_add_u64 v[18:19], v[18:19], 0, v[146:147]
	global_store_dwordx2 v[18:19], v[16:17], off
	v_mul_f32_e32 v16, 0x3d372713, v20
	v_mul_f32_e32 v16, v20, v16
	v_fma_f32 v16, v20, v16, v20
	v_mul_f32_e32 v16, 0x3f4c422a, v16
	v_add_f32_e32 v16, v16, v16
	v_mul_f32_e32 v16, 0x3fb8aa3b, v16
	v_exp_f32_e32 v16, v16
	v_mul_f32_e32 v17, 0.5, v20
	v_mul_f32_e32 v20, 0.5, v21
	v_add_f32_e32 v16, 1.0, v16
	v_rcp_f32_e32 v16, v16
	s_nop 0
	v_fma_f32 v16, v16, -2.0, 1.0
	v_add_f32_e32 v16, 1.0, v16
	v_mul_f32_e32 v16, v17, v16
	v_mul_f32_e32 v17, 0x3d372713, v21
	v_mul_f32_e32 v17, v21, v17
	v_fma_f32 v17, v21, v17, v21
	v_mul_f32_e32 v17, 0x3f4c422a, v17
	v_add_f32_e32 v17, v17, v17
	v_mul_f32_e32 v17, 0x3fb8aa3b, v17
	v_exp_f32_e32 v17, v17
	v_mul_f32_e32 v21, 0.5, v23
	v_add_f32_e32 v17, 1.0, v17
	v_rcp_f32_e32 v17, v17
	s_nop 0
	v_fma_f32 v17, v17, -2.0, 1.0
	v_add_f32_e32 v17, 1.0, v17
	v_mul_f32_e32 v17, v20, v17
	v_cvt_pk_bf16_f32 v16, v16, v17
	v_mul_f32_e32 v17, 0x3d372713, v22
	v_mul_f32_e32 v17, v22, v17
	v_fma_f32 v17, v22, v17, v22
	v_mul_f32_e32 v17, 0x3f4c422a, v17
	v_add_f32_e32 v17, v17, v17
	v_mul_f32_e32 v17, 0x3fb8aa3b, v17
	v_exp_f32_e32 v17, v17
	v_mul_f32_e32 v20, 0.5, v22
	v_add_f32_e32 v17, 1.0, v17
	v_rcp_f32_e32 v17, v17
	s_nop 0
	v_fma_f32 v17, v17, -2.0, 1.0
	v_add_f32_e32 v17, 1.0, v17
	v_mul_f32_e32 v17, v20, v17
	v_mul_f32_e32 v20, 0x3d372713, v23
	v_mul_f32_e32 v20, v23, v20
	v_fma_f32 v20, v23, v20, v23
	v_mul_f32_e32 v20, 0x3f4c422a, v20
	v_add_f32_e32 v20, v20, v20
	v_mul_f32_e32 v20, 0x3fb8aa3b, v20
	v_exp_f32_e32 v20, v20
	s_nop 0
	v_add_f32_e32 v20, 1.0, v20
	v_rcp_f32_e32 v20, v20
	s_nop 0
	v_fma_f32 v20, v20, -2.0, 1.0
	v_add_f32_e32 v20, 1.0, v20
	v_mul_f32_e32 v20, v21, v20
	v_cvt_pk_bf16_f32 v17, v17, v20
	global_store_dwordx2 v[18:19], v[16:17], off offset:16
	v_mul_f32_e32 v18, 0x3d372713, v24
	v_mul_f32_e32 v18, v24, v18
	v_fma_f32 v18, v24, v18, v24
	v_mul_f32_e32 v18, 0x3f4c422a, v18
	v_add_f32_e32 v18, v18, v18
	v_mul_f32_e32 v18, 0x3fb8aa3b, v18
	v_exp_f32_e32 v18, v18
	v_mul_f32_e32 v19, 0.5, v24
	v_mul_f32_e32 v20, 0.5, v25
	v_lshl_add_u64 v[16:17], v[34:35], 0, v[136:137]
	v_add_f32_e32 v18, 1.0, v18
	v_rcp_f32_e32 v18, v18
	v_lshlrev_b64 v[16:17], 10, v[16:17]
	v_lshl_add_u64 v[16:17], s[8:9], 0, v[16:17]
	v_mul_f32_e32 v21, 0.5, v27
	v_fma_f32 v18, v18, -2.0, 1.0
	v_add_f32_e32 v18, 1.0, v18
	v_mul_f32_e32 v18, v19, v18
	v_mul_f32_e32 v19, 0x3d372713, v25
	v_mul_f32_e32 v19, v25, v19
	v_fma_f32 v19, v25, v19, v25
	v_mul_f32_e32 v19, 0x3f4c422a, v19
	v_add_f32_e32 v19, v19, v19
	v_mul_f32_e32 v19, 0x3fb8aa3b, v19
	v_exp_f32_e32 v19, v19
	v_lshl_add_u64 v[16:17], v[16:17], 0, v[146:147]
	v_add_f32_e32 v19, 1.0, v19
	v_rcp_f32_e32 v19, v19
	s_nop 0
	v_fma_f32 v19, v19, -2.0, 1.0
	v_add_f32_e32 v19, 1.0, v19
	v_mul_f32_e32 v19, v20, v19
	v_cvt_pk_bf16_f32 v18, v18, v19
	v_mul_f32_e32 v19, 0x3d372713, v26
	v_mul_f32_e32 v19, v26, v19
	v_fma_f32 v19, v26, v19, v26
	v_mul_f32_e32 v19, 0x3f4c422a, v19
	v_add_f32_e32 v19, v19, v19
	v_mul_f32_e32 v19, 0x3fb8aa3b, v19
	v_exp_f32_e32 v19, v19
	v_mul_f32_e32 v20, 0.5, v26
	v_add_f32_e32 v19, 1.0, v19
	v_rcp_f32_e32 v19, v19
	s_nop 0
	v_fma_f32 v19, v19, -2.0, 1.0
	v_add_f32_e32 v19, 1.0, v19
	v_mul_f32_e32 v19, v20, v19
	v_mul_f32_e32 v20, 0x3d372713, v27
	v_mul_f32_e32 v20, v27, v20
	v_fma_f32 v20, v27, v20, v27
	v_mul_f32_e32 v20, 0x3f4c422a, v20
	v_add_f32_e32 v20, v20, v20
	v_mul_f32_e32 v20, 0x3fb8aa3b, v20
	v_exp_f32_e32 v20, v20
	s_nop 0
	v_add_f32_e32 v20, 1.0, v20
	v_rcp_f32_e32 v20, v20
	s_nop 0
	v_fma_f32 v20, v20, -2.0, 1.0
	v_add_f32_e32 v20, 1.0, v20
	v_mul_f32_e32 v20, v21, v20
	v_cvt_pk_bf16_f32 v19, v19, v20
	global_store_dwordx2 v[16:17], v[18:19], off
	v_mul_f32_e32 v18, 0x3d372713, v28
	v_mul_f32_e32 v18, v28, v18
	v_fma_f32 v18, v28, v18, v28
	v_mul_f32_e32 v18, 0x3f4c422a, v18
	v_add_f32_e32 v18, v18, v18
	v_mul_f32_e32 v18, 0x3fb8aa3b, v18
	v_exp_f32_e32 v18, v18
	v_mul_f32_e32 v19, 0.5, v28
	v_mul_f32_e32 v20, 0.5, v29
	v_mul_f32_e32 v21, 0.5, v31
	v_add_f32_e32 v18, 1.0, v18
	v_rcp_f32_e32 v18, v18
	s_nop 0
	v_fma_f32 v18, v18, -2.0, 1.0
	v_add_f32_e32 v18, 1.0, v18
	v_mul_f32_e32 v18, v19, v18
	v_mul_f32_e32 v19, 0x3d372713, v29
	v_mul_f32_e32 v19, v29, v19
	v_fma_f32 v19, v29, v19, v29
	v_mul_f32_e32 v19, 0x3f4c422a, v19
	v_add_f32_e32 v19, v19, v19
	v_mul_f32_e32 v19, 0x3fb8aa3b, v19
	v_exp_f32_e32 v19, v19
	s_nop 0
	v_add_f32_e32 v19, 1.0, v19
	v_rcp_f32_e32 v19, v19
	s_nop 0
	v_fma_f32 v19, v19, -2.0, 1.0
	v_add_f32_e32 v19, 1.0, v19
	v_mul_f32_e32 v19, v20, v19
	v_cvt_pk_bf16_f32 v18, v18, v19
	v_mul_f32_e32 v19, 0x3d372713, v30
	v_mul_f32_e32 v19, v30, v19
	v_fma_f32 v19, v30, v19, v30
	v_mul_f32_e32 v19, 0x3f4c422a, v19
	v_add_f32_e32 v19, v19, v19
	v_mul_f32_e32 v19, 0x3fb8aa3b, v19
	v_exp_f32_e32 v19, v19
	v_mul_f32_e32 v20, 0.5, v30
	v_add_f32_e32 v19, 1.0, v19
	v_rcp_f32_e32 v19, v19
	s_nop 0
	v_fma_f32 v19, v19, -2.0, 1.0
	v_add_f32_e32 v19, 1.0, v19
	v_mul_f32_e32 v19, v20, v19
	v_mul_f32_e32 v20, 0x3d372713, v31
	v_mul_f32_e32 v20, v31, v20
	v_fma_f32 v20, v31, v20, v31
	v_mul_f32_e32 v20, 0x3f4c422a, v20
	v_add_f32_e32 v20, v20, v20
	v_mul_f32_e32 v20, 0x3fb8aa3b, v20
	v_exp_f32_e32 v20, v20
	s_nop 0
	v_add_f32_e32 v20, 1.0, v20
	v_rcp_f32_e32 v20, v20
	s_nop 0
	v_fma_f32 v20, v20, -2.0, 1.0
	v_add_f32_e32 v20, 1.0, v20
	v_mul_f32_e32 v20, v21, v20
	v_cvt_pk_bf16_f32 v19, v19, v20
	v_mul_f32_e32 v20, 0x3d372713, v0
	v_mul_f32_e32 v20, v0, v20
	v_fma_f32 v20, v0, v20, v0
	v_mul_f32_e32 v20, 0x3f4c422a, v20
	v_add_f32_e32 v20, v20, v20
	v_mul_f32_e32 v20, 0x3fb8aa3b, v20
	v_exp_f32_e32 v20, v20
	v_mul_f32_e32 v0, 0.5, v0
	global_store_dwordx2 v[16:17], v[18:19], off offset:16
	v_mov_b32_e32 v17, s11
	v_add_f32_e32 v20, 1.0, v20
	v_rcp_f32_e32 v20, v20
	v_or_b32_e32 v16, s10, v142
	v_lshl_add_u64 v[18:19], v[16:17], 0, v[114:115]
	v_fma_f32 v20, v20, -2.0, 1.0
	v_add_f32_e32 v20, 1.0, v20
	v_mul_f32_e32 v0, v0, v20
	v_mul_f32_e32 v20, 0x3d372713, v1
	v_mul_f32_e32 v20, v1, v20
	v_fma_f32 v20, v1, v20, v1
	v_mul_f32_e32 v20, 0x3f4c422a, v20
	v_add_f32_e32 v20, v20, v20
	v_mul_f32_e32 v20, 0x3fb8aa3b, v20
	v_exp_f32_e32 v20, v20
	v_mul_f32_e32 v1, 0.5, v1
	v_add_f32_e32 v20, 1.0, v20
	v_rcp_f32_e32 v20, v20
	s_nop 0
	v_fma_f32 v20, v20, -2.0, 1.0
	v_add_f32_e32 v20, 1.0, v20
	v_mul_f32_e32 v1, v1, v20
	v_cvt_pk_bf16_f32 v0, v0, v1
	v_mul_f32_e32 v1, 0x3d372713, v2
	v_mul_f32_e32 v1, v2, v1
	v_fma_f32 v1, v2, v1, v2
	v_mul_f32_e32 v1, 0x3f4c422a, v1
	v_add_f32_e32 v1, v1, v1
	v_mul_f32_e32 v1, 0x3fb8aa3b, v1
	v_exp_f32_e32 v1, v1
	v_mul_f32_e32 v2, 0.5, v2
	v_add_f32_e32 v1, 1.0, v1
	v_rcp_f32_e32 v1, v1
	s_nop 0
	v_fma_f32 v1, v1, -2.0, 1.0
	v_add_f32_e32 v1, 1.0, v1
	v_mul_f32_e32 v1, v2, v1
	v_mul_f32_e32 v2, 0x3d372713, v3
	v_mul_f32_e32 v2, v3, v2
	v_fma_f32 v2, v3, v2, v3
	v_mul_f32_e32 v2, 0x3f4c422a, v2
	v_add_f32_e32 v2, v2, v2
	v_mul_f32_e32 v2, 0x3fb8aa3b, v2
	v_exp_f32_e32 v2, v2
	v_mul_f32_e32 v3, 0.5, v3
	v_add_f32_e32 v2, 1.0, v2
	v_rcp_f32_e32 v2, v2
	s_nop 0
	v_fma_f32 v2, v2, -2.0, 1.0
	v_add_f32_e32 v2, 1.0, v2
	v_mul_f32_e32 v2, v3, v2
	v_cvt_pk_bf16_f32 v1, v1, v2
	v_lshlrev_b64 v[2:3], 10, v[18:19]
	v_lshl_add_u64 v[2:3], s[8:9], 0, v[2:3]
	v_lshl_add_u64 v[2:3], v[2:3], 0, v[146:147]
	global_store_dwordx2 v[2:3], v[0:1], off
	v_mul_f32_e32 v0, 0x3d372713, v4
	v_mul_f32_e32 v0, v4, v0
	v_fma_f32 v0, v4, v0, v4
	v_mul_f32_e32 v0, 0x3f4c422a, v0
	v_add_f32_e32 v0, v0, v0
	v_mul_f32_e32 v0, 0x3fb8aa3b, v0
	v_exp_f32_e32 v0, v0
	v_mul_f32_e32 v1, 0.5, v4
	v_mul_f32_e32 v4, 0.5, v5
	v_add_f32_e32 v0, 1.0, v0
	v_rcp_f32_e32 v0, v0
	s_nop 0
	v_fma_f32 v0, v0, -2.0, 1.0
	v_add_f32_e32 v0, 1.0, v0
	v_mul_f32_e32 v0, v1, v0
	v_mul_f32_e32 v1, 0x3d372713, v5
	v_mul_f32_e32 v1, v5, v1
	v_fma_f32 v1, v5, v1, v5
	v_mul_f32_e32 v1, 0x3f4c422a, v1
	v_add_f32_e32 v1, v1, v1
	v_mul_f32_e32 v1, 0x3fb8aa3b, v1
	v_exp_f32_e32 v1, v1
	v_mul_f32_e32 v5, 0.5, v7
	v_add_f32_e32 v1, 1.0, v1
	v_rcp_f32_e32 v1, v1
	s_nop 0
	v_fma_f32 v1, v1, -2.0, 1.0
	v_add_f32_e32 v1, 1.0, v1
	v_mul_f32_e32 v1, v4, v1
	v_cvt_pk_bf16_f32 v0, v0, v1
	v_mul_f32_e32 v1, 0x3d372713, v6
	v_mul_f32_e32 v1, v6, v1
	v_fma_f32 v1, v6, v1, v6
	v_mul_f32_e32 v1, 0x3f4c422a, v1
	v_add_f32_e32 v1, v1, v1
	v_mul_f32_e32 v1, 0x3fb8aa3b, v1
	v_exp_f32_e32 v1, v1
	v_mul_f32_e32 v4, 0.5, v6
	v_add_f32_e32 v1, 1.0, v1
	v_rcp_f32_e32 v1, v1
	s_nop 0
	v_fma_f32 v1, v1, -2.0, 1.0
	v_add_f32_e32 v1, 1.0, v1
	v_mul_f32_e32 v1, v4, v1
	v_mul_f32_e32 v4, 0x3d372713, v7
	v_mul_f32_e32 v4, v7, v4
	v_fma_f32 v4, v7, v4, v7
	v_mul_f32_e32 v4, 0x3f4c422a, v4
	v_add_f32_e32 v4, v4, v4
	v_mul_f32_e32 v4, 0x3fb8aa3b, v4
	v_exp_f32_e32 v4, v4
	s_nop 0
	v_add_f32_e32 v4, 1.0, v4
	v_rcp_f32_e32 v4, v4
	s_nop 0
	v_fma_f32 v4, v4, -2.0, 1.0
	v_add_f32_e32 v4, 1.0, v4
	v_mul_f32_e32 v4, v5, v4
	v_cvt_pk_bf16_f32 v1, v1, v4
	global_store_dwordx2 v[2:3], v[0:1], off offset:16
	v_mul_f32_e32 v2, 0x3d372713, v8
	v_mul_f32_e32 v2, v8, v2
	v_fma_f32 v2, v8, v2, v8
	v_mul_f32_e32 v2, 0x3f4c422a, v2
	v_add_f32_e32 v2, v2, v2
	v_mul_f32_e32 v2, 0x3fb8aa3b, v2
	v_exp_f32_e32 v2, v2
	v_mul_f32_e32 v3, 0.5, v8
	v_mul_f32_e32 v4, 0.5, v9
	v_lshl_add_u64 v[0:1], v[16:17], 0, v[136:137]
	v_add_f32_e32 v2, 1.0, v2
	v_rcp_f32_e32 v2, v2
	v_lshlrev_b64 v[0:1], 10, v[0:1]
	v_lshl_add_u64 v[0:1], s[8:9], 0, v[0:1]
	v_mul_f32_e32 v5, 0.5, v11
	v_fma_f32 v2, v2, -2.0, 1.0
	v_add_f32_e32 v2, 1.0, v2
	v_mul_f32_e32 v2, v3, v2
	v_mul_f32_e32 v3, 0x3d372713, v9
	v_mul_f32_e32 v3, v9, v3
	v_fma_f32 v3, v9, v3, v9
	v_mul_f32_e32 v3, 0x3f4c422a, v3
	v_add_f32_e32 v3, v3, v3
	v_mul_f32_e32 v3, 0x3fb8aa3b, v3
	v_exp_f32_e32 v3, v3
	v_lshl_add_u64 v[0:1], v[0:1], 0, v[146:147]
	v_add_f32_e32 v3, 1.0, v3
	v_rcp_f32_e32 v3, v3
	s_nop 0
	v_fma_f32 v3, v3, -2.0, 1.0
	v_add_f32_e32 v3, 1.0, v3
	v_mul_f32_e32 v3, v4, v3
	v_cvt_pk_bf16_f32 v2, v2, v3
	v_mul_f32_e32 v3, 0x3d372713, v10
	v_mul_f32_e32 v3, v10, v3
	v_fma_f32 v3, v10, v3, v10
	v_mul_f32_e32 v3, 0x3f4c422a, v3
	v_add_f32_e32 v3, v3, v3
	v_mul_f32_e32 v3, 0x3fb8aa3b, v3
	v_exp_f32_e32 v3, v3
	v_mul_f32_e32 v4, 0.5, v10
	v_add_f32_e32 v3, 1.0, v3
	v_rcp_f32_e32 v3, v3
	s_nop 0
	v_fma_f32 v3, v3, -2.0, 1.0
	v_add_f32_e32 v3, 1.0, v3
	v_mul_f32_e32 v3, v4, v3
	v_mul_f32_e32 v4, 0x3d372713, v11
	v_mul_f32_e32 v4, v11, v4
	v_fma_f32 v4, v11, v4, v11
	v_mul_f32_e32 v4, 0x3f4c422a, v4
	v_add_f32_e32 v4, v4, v4
	v_mul_f32_e32 v4, 0x3fb8aa3b, v4
	v_exp_f32_e32 v4, v4
	s_nop 0
	v_add_f32_e32 v4, 1.0, v4
	v_rcp_f32_e32 v4, v4
	s_nop 0
	v_fma_f32 v4, v4, -2.0, 1.0
	v_add_f32_e32 v4, 1.0, v4
	v_mul_f32_e32 v4, v5, v4
	v_cvt_pk_bf16_f32 v3, v3, v4
	global_store_dwordx2 v[0:1], v[2:3], off
	v_mul_f32_e32 v2, 0x3d372713, v12
	v_mul_f32_e32 v2, v12, v2
	v_fma_f32 v2, v12, v2, v12
	v_mul_f32_e32 v2, 0x3f4c422a, v2
	v_add_f32_e32 v2, v2, v2
	v_mul_f32_e32 v2, 0x3fb8aa3b, v2
	v_exp_f32_e32 v2, v2
	v_mul_f32_e32 v3, 0.5, v12
	v_mul_f32_e32 v4, 0.5, v13
	v_mul_f32_e32 v5, 0.5, v15
	v_add_f32_e32 v2, 1.0, v2
	v_rcp_f32_e32 v2, v2
	s_nop 0
	v_fma_f32 v2, v2, -2.0, 1.0
	v_add_f32_e32 v2, 1.0, v2
	v_mul_f32_e32 v2, v3, v2
	v_mul_f32_e32 v3, 0x3d372713, v13
	v_mul_f32_e32 v3, v13, v3
	v_fma_f32 v3, v13, v3, v13
	v_mul_f32_e32 v3, 0x3f4c422a, v3
	v_add_f32_e32 v3, v3, v3
	v_mul_f32_e32 v3, 0x3fb8aa3b, v3
	v_exp_f32_e32 v3, v3
	s_nop 0
	v_add_f32_e32 v3, 1.0, v3
	v_rcp_f32_e32 v3, v3
	s_nop 0
	v_fma_f32 v3, v3, -2.0, 1.0
	v_add_f32_e32 v3, 1.0, v3
	v_mul_f32_e32 v3, v4, v3
	v_cvt_pk_bf16_f32 v2, v2, v3
	v_mul_f32_e32 v3, 0x3d372713, v14
	v_mul_f32_e32 v3, v14, v3
	v_fma_f32 v3, v14, v3, v14
	v_mul_f32_e32 v3, 0x3f4c422a, v3
	v_add_f32_e32 v3, v3, v3
	v_mul_f32_e32 v3, 0x3fb8aa3b, v3
	v_exp_f32_e32 v3, v3
	v_mul_f32_e32 v4, 0.5, v14
	v_add_f32_e32 v3, 1.0, v3
	v_rcp_f32_e32 v3, v3
	s_nop 0
	v_fma_f32 v3, v3, -2.0, 1.0
	v_add_f32_e32 v3, 1.0, v3
	v_mul_f32_e32 v3, v4, v3
	v_mul_f32_e32 v4, 0x3d372713, v15
	v_mul_f32_e32 v4, v15, v4
	v_fma_f32 v4, v15, v4, v15
	v_mul_f32_e32 v4, 0x3f4c422a, v4
	v_add_f32_e32 v4, v4, v4
	v_mul_f32_e32 v4, 0x3fb8aa3b, v4
	v_exp_f32_e32 v4, v4
	s_nop 0
	v_add_f32_e32 v4, 1.0, v4
	v_rcp_f32_e32 v4, v4
	s_nop 0
	v_fma_f32 v4, v4, -2.0, 1.0
	v_add_f32_e32 v4, 1.0, v4
	v_mul_f32_e32 v4, v5, v4
	v_cvt_pk_bf16_f32 v3, v3, v4
	global_store_dwordx2 v[0:1], v[2:3], off offset:16
	s_cbranch_scc0 .LBB0_718
